# static s_setprio 2 for waves 4-7 (second wave per SIMD) during attention and xattn phases
# baseline (speedup 1.0000x reference)
; DI void phase_mixA(const Params& p, char* lds) {
;     ...
;   if ((gridDim.x & 7) == 0 && gridDim.x <= 256) {
;     const int x = blockIdx.x & 7, slot = blockIdx.x >> 3, nx = gridDim.x >> 3;
;     for (int j = slot; j < 256; j += nx) attn_item(p, lds, x * 256 + j);
.LBB0_342:
	v_readfirstlane_b32 s32, v222
	s_nop 3
	s_cmp_lt_u32 s32, 0x100
	s_cbranch_scc1 .Lprio_att
	s_setprio 2

; DI int otid() { int t = __builtin_amdgcn_workitem_id_x(); asm volatile("" : "+v"(t)); return t; }
; DI void phase_mlstm_scan(const Params& p) {
;   char* ws = p.ws;
;   const int tid = otid();
;   for (int unit = blockIdx.x; unit < 256; unit += gridDim.x) {
;     const int bh = unit >> 3, part = unit & 7;
;     u16* kv = (u16*)(ws + OFF_KVS) + (size_t)bh * 128 * 16384 + part * 2048 + tid * 4;
;     float* ks = (float*)(ws + OFF_KSUM) + (size_t)bh * 128 * 128 + tid;
;     float* csc = (float*)(ws + OFF_CSC) + (size_t)bh * 128 * 4;
;     const bool don = (part == 0) && (tid < 128);
;     float m = 0.f, c0 = 0.f, c1 = 0.f, c2 = 0.f, c3 = 0.f, n = 0.f;
; #pragma unroll 1
;     for (int cb = 0; cb < 128; cb += 8) {
.LBB0_462:
	s_or_b64 exec, exec, s[0:1]
	s_setprio 0
	v_readlane_b32 s0, v250, 21
	v_readlane_b32 s1, v250, 22
	s_waitcnt lgkmcnt(0)
	v_mov_b32_e32 v0, v222
	s_and_b64 vcc, exec, s[0:1]
	s_barrier
	s_cbranch_vccnz .LBB0_515
	v_lshlrev_b32_e32 v4, 2, v0
	v_ashrrev_i32_e32 v5, 31, v4
	v_ashrrev_i32_e32 v1, 31, v0
	s_movk_i32 s0, 0x80
	v_cmp_gt_i32_e64 s[0:1], s0, v0
	v_lshlrev_b64 v[2:3], 2, v[0:1]
	v_lshlrev_b64 v[4:5], 1, v[4:5]
	s_mov_b64 s[6:7], 0x32828000
	s_mov_b64 s[8:9], 0x32830000
	s_mov_b64 s[10:11], 0x32838000
	v_mov_b32_e32 v1, 0x3aa00000
	s_mov_b64 s[12:13], 0x1000
	s_mov_b64 s[14:15], 0x40000
	s_mov_b32 s2, s94
	s_mov_b32 s22, s94
	s_branch .LBB0_465

; DI int otid() { int t = __builtin_amdgcn_workitem_id_x(); asm volatile("" : "+v"(t)); return t; }
; DI int perm23(int i) { return (i & 0x13) | (((i >> 3) & 1) << 2) | (((i >> 2) & 1) << 3); }
; DI f32x16 zero16() { f32x16 z; for (int i = 0; i < 16; ++i) z[i] = 0.f; return z; }
; DI void phase_xattn(const Params& p, char* lds) {
;     ...
;   const int tid = otid(), lane = tid & 63, wave = tid >> 6, l31 = lane & 31, hh = lane >> 5;
;   const u16* XQ = (const u16*)(ws + OFF_XQ); const u16* KX = (const u16*)(ws + OFF_KX); const u16* VTX = (const u16*)(ws + OFF_VTX);
;   u16* XO = (u16*)(ws + OFF_XO);
;   u16* Kl = (u16*)lds; u16* Vl = Kl + 2 * 32 * 264;
;   const int pi = perm23(l31);
;   const int kr0 = tid >> 5, kc = (tid & 31) * 8, vr = tid >> 2, vc = (tid & 3) * 8;
;   for (int item = blockIdx.x; item < 1024; item += gridDim.x) {
;     const int b = item >> 7, h = (item >> 5) & 3, qblk = item & 31;
;     const size_t q0 = (size_t)b * SEQ + qblk * 256 + wave * 32;
;     bf16x8 Qf[16];
; #pragma unroll
;     for (int kk = 0; kk < 16; ++kk) Qf[kk] = ldfrag(XQ + (q0 + l31) * 1024 + h * 256 + kk * 16 + 8 * hh);
;     const u16* kg = KX + ((size_t)b * 256) * 1024 + h * 256;
;     const u16* vg = VTX + ((size_t)((b * 4 + h) * 256)) * 256;
;     {
;       const uint4 k0 = *(const uint4*)(kg + (size_t)kr0 * 1024 + kc), k1 = *(const uint4*)(kg + (size_t)(kr0 + 16) * 1024 + kc);
;       const uint4 v0 = *(const uint4*)(vg + (size_t)vr * 256 + vc);
;       *(uint4*)(Kl + kr0 * 264 + kc) = k0; *(uint4*)(Kl + (kr0 + 16) * 264 + kc) = k1; *(uint4*)(Vl + vr * 40 + vc) = v0;
;     }
;     __syncthreads();
;     f32x16 O[4]; for (int i = 0; i < 4; ++i) O[i] = zero16();
;     float mrun = -INFINITY, lrun = 0.f;
.LBB0_900:
	s_or_b64 exec, exec, s[4:5]
	v_readfirstlane_b32 s32, v222
	s_nop 3
	s_cmp_lt_u32 s32, 0x100
	s_cbranch_scc1 .Lprio_xat
	s_setprio 2
.Lprio_xat:
	s_cmpk_lt_i32 s94, 0x400
	s_waitcnt lgkmcnt(0)
	v_mov_b32_e32 v0, v222
	s_cselect_b64 s[4:5], -1, 0
	s_cmpk_gt_i32 s94, 0x3ff
	s_barrier
	s_cbranch_scc1 .LBB0_911
	v_ashrrev_i32_e32 v156, 5, v0
	v_lshlrev_b32_e32 v1, 3, v0
	v_lshrrev_b32_e32 v4, 1, v0
	v_lshlrev_b32_e32 v6, 1, v0
	s_movk_i32 s2, 0x210
	v_ashrrev_i32_e32 v160, 2, v0
	v_and_b32_e32 v2, 24, v1
	v_and_b32_e32 v3, 19, v0
	v_and_b32_e32 v4, 4, v4
	v_and_b32_e32 v6, 8, v6
	v_ashrrev_i32_e32 v157, 31, v156
	v_mul_lo_u32 v7, v156, s2
	s_movk_i32 s2, 0x50
	v_and_b32_e32 v158, 0xf8, v1
	v_lshlrev_b32_e32 v1, 1, v2
	v_or3_b32 v3, v3, v4, v6
	v_bfe_u32 v4, v0, 5, 1
	v_lshlrev_b64 v[166:167], 11, v[156:157]
	v_ashrrev_i32_e32 v161, 31, v160
	v_add_u32_e32 v157, 0, v7
	v_mul_lo_u32 v7, v160, s2
	v_and_b32_e32 v5, 31, v0
	v_lshlrev_b64 v[170:171], 9, v[160:161]
	v_add3_u32 v161, 0, v1, v7
	v_mul_u32_u24_e32 v1, 0x210, v3
	v_lshlrev_b32_e32 v3, 4, v4
	v_add3_u32 v182, 0, v1, v3
	v_mul_u32_u24_e32 v1, 0x50, v5
	v_add3_u32 v183, 0, v1, v3
	v_mbcnt_hi_u32_b32 v1, -1, v203
	v_and_b32_e32 v7, 64, v1
	v_xor_b32_e32 v3, 32, v1
	v_add_u32_e32 v7, 64, v7
	v_ashrrev_i32_e32 v0, 1, v0
	v_cmp_lt_i32_e32 vcc, v3, v7
	v_and_b32_e32 v6, 0xffffffe0, v0
	v_lshlrev_b32_e32 v0, 3, v4
	v_mov_b32_e32 v165, 0
	s_mov_b64 s[8:9], 0x8000
	v_cndmask_b32_e32 v1, v1, v3, vcc
	v_lshlrev_b32_e32 v4, 2, v4
	s_mov_b32 s7, 0
	v_ashrrev_i32_e32 v163, 31, v6
	v_lshl_add_u64 v[168:169], v[166:167], 0, s[8:9]
	v_lshl_add_u32 v159, v158, 1, v157
	v_lshlrev_b32_e32 v184, 2, v1
	v_or_b32_e32 v162, v6, v5
	v_lshlrev_b32_e32 v172, 1, v0
	v_mov_b32_e32 v173, v165
	v_lshlrev_b32_e32 v174, 1, v158
	v_mov_b32_e32 v175, v165
	v_lshlrev_b32_e32 v164, 1, v2
	v_lshlrev_b32_e32 v176, 1, v4
	v_mov_b32_e32 v177, v165
	s_mov_b32 s2, 0x3db8aa3b
	s_mov_b32 s12, 0xff800000
	s_mov_b32 s13, s94
	s_branch .LBB0_903

; DI bool tile_of(int it, int MT, int NT, int& mt, int& nt) {
;   const int nb = gridDim.x;
;   if ((nb & 7) == 0 && (MT & 7) == 0) {
;     const int x = blockIdx.x & 7, slot = blockIdx.x >> 3, nx = nb >> 3, j = slot + it * nx, per = (MT >> 3) * NT;
;     if (j >= per) return false;
;     if (NT == 14 && (MT >> 3) == 32) {
;       const int r = j / 28, w = j - r * 28, nh = r >> 3, mg = r & 7;
;       mt = x * 32 + mg * 4 + w / 7; nt = nh * 7 + w % 7; return true;
;     }
;     mt = x * (MT >> 3) + j / NT; nt = j % NT; return true;
;   }
;   const int j = blockIdx.x + it * nb;
;   if (j >= MT * NT) return false;
;   mt = j / NT; nt = j % NT; return true;
; template <int MODE>
; DI void phase_gemm1024(const u16* __restrict__ A, const u16* __restrict__ Wt, u16* __restrict__ dstb, const u16* __restrict__ Hres, char* lds) {
;     ...
;   int mt, nt; bool have = tile_of(0, 256, 4, mt, nt);
;   for (int it = 0; have; ++it) {
;     const int m0 = mt * 256, n0 = nt * 256;
.LBB0_963:
	s_or_b64 exec, exec, s[0:1]
	s_setprio 0
	s_waitcnt lgkmcnt(0)
	v_mov_b32_e32 v0, v222
	s_and_b64 vcc, exec, s[28:29]
	s_barrier
	s_cbranch_vccz .LBB0_967
	s_mov_b64 s[6:7], 0
	s_and_b64 vcc, exec, s[4:5]
	s_mov_b64 s[0:1], 0
	s_cbranch_vccz .LBB0_966
	s_ashr_i32 s0, s94, 31
	s_lshr_b32 s0, s0, 30
	s_add_i32 s0, s94, s0
	s_ashr_i32 s23, s0, 2
	s_and_b32 s0, s0, -4
	s_sub_i32 s22, s94, s0
	s_lshl_b32 s0, s94, 5
	s_and_b32 s2, s0, 0xe0
	s_mov_b64 s[0:1], -1
